# attention softmax: cross-half row-max exchange via v_permlane32_swap instead of an LDS-crossbar ds_bpermute round trip
# speedup vs baseline: 1.0833x; 1.0056x over previous
.LBB0_275:
	s_nop 0
	v_and_b32_e32 v2, 64, v224
	v_xor_b32_e32 v198, 32, v224
	v_add_u32_e32 v230, 64, v2
	v_cmp_lt_i32_e32 vcc, v198, v230
	v_cndmask_b32_e64 v3, 0, 1, s[16:17]
	v_cmp_ne_u32_e64 s[36:37], 1, v3
	v_cndmask_b32_e32 v2, v224, v198, vcc
	v_lshlrev_b32_e32 v247, 2, v2
	v_mov_b32_e32 v2, v178
	v_mov_b32_e32 v3, v178
	s_andn2_b64 vcc, exec, s[16:17]
	s_mov_b64 s[16:17], -1
	s_waitcnt lgkmcnt(0)
	v_permlane32_swap_b32_e32 v2, v3
	v_max_f32_e32 v2, v2, v3
	v_max3_f32 v179, v221, v178, v2
	s_cbranch_vccnz .LBB0_277
	v_sub_f32_e32 v2, v218, v179
	v_exp_f32_e32 v2, v2
	v_sub_f32_e32 v3, v219, v179
	v_exp_f32_e32 v3, v3
	v_sub_f32_e32 v4, v216, v179
	v_exp_f32_e32 v4, v4
	v_sub_f32_e32 v5, v217, v179
	v_exp_f32_e32 v5, v5
	v_add_f32_e32 v6, 0, v2
	v_add_f32_e32 v6, v3, v6
	v_add_f32_e32 v6, v4, v6
	v_add_f32_e32 v10, v5, v6
	v_sub_f32_e32 v6, v214, v179
	v_exp_f32_e32 v6, v6
	v_sub_f32_e32 v7, v215, v179
	v_exp_f32_e32 v7, v7
	v_sub_f32_e32 v8, v208, v179
	v_exp_f32_e32 v8, v8
	v_sub_f32_e32 v9, v209, v179
	v_exp_f32_e32 v9, v9
	v_add_f32_e32 v10, v6, v10
	v_add_f32_e32 v10, v7, v10
	v_add_f32_e32 v10, v8, v10
	v_add_f32_e32 v14, v9, v10
	v_sub_f32_e32 v10, v212, v179
	v_exp_f32_e32 v10, v10
	v_sub_f32_e32 v11, v213, v179
	v_exp_f32_e32 v11, v11
	v_sub_f32_e32 v12, v206, v179
	v_exp_f32_e32 v12, v12
	v_sub_f32_e32 v13, v207, v179
	v_exp_f32_e32 v13, v13
	v_add_f32_e32 v14, v10, v14
	v_add_f32_e32 v14, v11, v14
	v_add_f32_e32 v14, v12, v14
	v_add_f32_e32 v18, v13, v14
	v_sub_f32_e32 v14, v202, v179
	v_exp_f32_e32 v14, v14
	v_sub_f32_e32 v15, v203, v179
	v_exp_f32_e32 v15, v15
	v_sub_f32_e32 v16, v192, v179
	v_exp_f32_e32 v16, v16
	v_sub_f32_e32 v17, v193, v179
	v_exp_f32_e32 v17, v17
	v_add_f32_e32 v18, v14, v18
	v_add_f32_e32 v18, v15, v18
	v_add_f32_e32 v18, v16, v18
	v_add_f32_e32 v22, v17, v18
	v_sub_f32_e32 v18, v210, v179
	v_exp_f32_e32 v18, v18
	v_sub_f32_e32 v19, v211, v179
	v_exp_f32_e32 v19, v19
	v_sub_f32_e32 v20, v204, v179
	v_exp_f32_e32 v20, v20
	v_sub_f32_e32 v21, v205, v179
	v_exp_f32_e32 v21, v21
	v_add_f32_e32 v22, v18, v22
	v_add_f32_e32 v22, v19, v22
	v_add_f32_e32 v22, v20, v22
	v_add_f32_e32 v26, v21, v22
	v_sub_f32_e32 v22, v194, v179
	v_exp_f32_e32 v22, v22
	v_sub_f32_e32 v23, v195, v179
	v_exp_f32_e32 v23, v23
	v_sub_f32_e32 v24, v190, v179
	v_exp_f32_e32 v24, v24
	v_sub_f32_e32 v25, v191, v179
	v_exp_f32_e32 v25, v25
	v_add_f32_e32 v26, v22, v26
	v_add_f32_e32 v26, v23, v26
	v_add_f32_e32 v26, v24, v26
	v_add_f32_e32 v30, v25, v26
	v_sub_f32_e32 v26, v188, v179
	v_exp_f32_e32 v26, v26
	v_sub_f32_e32 v27, v189, v179
	v_exp_f32_e32 v27, v27
	v_sub_f32_e32 v28, v186, v179
	v_exp_f32_e32 v28, v28
	v_sub_f32_e32 v29, v187, v179
	v_exp_f32_e32 v29, v29
	v_add_f32_e32 v30, v26, v30
	v_add_f32_e32 v30, v27, v30
	v_add_f32_e32 v30, v28, v30
	v_add_f32_e32 v33, v29, v30
	v_sub_f32_e32 v30, v184, v179
	v_exp_f32_e32 v30, v30
	v_sub_f32_e32 v31, v185, v179
	v_exp_f32_e32 v31, v31
	v_sub_f32_e32 v32, v182, v179
	v_exp_f32_e32 v32, v32
	v_add_f32_e32 v33, v30, v33
	v_add_f32_e32 v178, v31, v33
	v_pk_add_f32 v[180:181], v[182:183], v[178:179] neg_lo:[0,1] neg_hi:[0,1]
	s_mov_b64 s[16:17], 0
	v_add_f32_e32 v180, v32, v178

.LBB0_285:
	s_nop 5
	v_mov_b32_e32 v2, v183
	v_mov_b32_e32 v3, v183
	s_and_b64 vcc, exec, s[36:37]
	s_mov_b64 s[36:37], -1
	s_waitcnt lgkmcnt(0)
	v_permlane32_swap_b32_e32 v2, v3
	v_max_f32_e32 v2, v2, v3
	v_max3_f32 v231, v197, v183, v2
	s_cbranch_vccnz .LBB0_287
	v_sub_f32_e32 v2, v190, v231
	v_exp_f32_e32 v2, v2
	v_sub_f32_e32 v3, v191, v231
	v_exp_f32_e32 v3, v3
	v_sub_f32_e32 v4, v188, v231
	v_exp_f32_e32 v4, v4
	v_add_f32_e32 v5, 0, v2
	v_add_f32_e32 v5, v3, v5
	v_sub_f32_e32 v6, v186, v231
	v_add_f32_e32 v9, v4, v5
	v_sub_f32_e32 v5, v189, v231
	v_exp_f32_e32 v5, v5
	v_exp_f32_e32 v6, v6
	v_sub_f32_e32 v7, v187, v231
	v_exp_f32_e32 v7, v7
	v_sub_f32_e32 v8, v184, v231
	v_exp_f32_e32 v8, v8
	v_add_f32_e32 v9, v5, v9
	v_add_f32_e32 v9, v6, v9
	v_add_f32_e32 v9, v7, v9
	v_add_f32_e32 v13, v8, v9
	v_sub_f32_e32 v9, v185, v231
	v_exp_f32_e32 v9, v9
	v_sub_f32_e32 v10, v204, v231
	v_exp_f32_e32 v10, v10
	v_sub_f32_e32 v11, v205, v231
	v_exp_f32_e32 v11, v11
	v_sub_f32_e32 v12, v202, v231
	v_exp_f32_e32 v12, v12
	v_add_f32_e32 v13, v9, v13
	v_add_f32_e32 v13, v10, v13
	v_add_f32_e32 v13, v11, v13
	v_add_f32_e32 v17, v12, v13
	v_sub_f32_e32 v13, v203, v231
	v_exp_f32_e32 v13, v13
	v_sub_f32_e32 v14, v194, v231
	v_exp_f32_e32 v14, v14
	v_sub_f32_e32 v15, v195, v231
	v_exp_f32_e32 v15, v15
	v_sub_f32_e32 v16, v192, v231
	v_exp_f32_e32 v16, v16
	v_add_f32_e32 v17, v13, v17
	v_add_f32_e32 v17, v14, v17
	v_add_f32_e32 v17, v15, v17
	v_add_f32_e32 v21, v16, v17
	v_sub_f32_e32 v17, v193, v231
	v_exp_f32_e32 v17, v17
	v_sub_f32_e32 v18, v220, v231
	v_exp_f32_e32 v18, v18
	v_sub_f32_e32 v19, v221, v231
	v_exp_f32_e32 v19, v19
	v_sub_f32_e32 v20, v218, v231
	v_exp_f32_e32 v20, v20
	v_add_f32_e32 v21, v17, v21
	v_add_f32_e32 v21, v18, v21
	v_add_f32_e32 v21, v19, v21
	v_add_f32_e32 v25, v20, v21
	v_sub_f32_e32 v21, v219, v231
	v_exp_f32_e32 v21, v21
	v_sub_f32_e32 v22, v216, v231
	v_exp_f32_e32 v22, v22
	v_sub_f32_e32 v23, v217, v231
	v_exp_f32_e32 v23, v23
	v_sub_f32_e32 v24, v214, v231
	v_exp_f32_e32 v24, v24
	v_add_f32_e32 v25, v21, v25
	v_add_f32_e32 v25, v22, v25
	v_add_f32_e32 v25, v23, v25
	v_add_f32_e32 v29, v24, v25
	v_sub_f32_e32 v25, v215, v231
	v_exp_f32_e32 v25, v25
	v_sub_f32_e32 v26, v212, v231
	v_exp_f32_e32 v26, v26
	v_sub_f32_e32 v27, v213, v231
	v_exp_f32_e32 v27, v27
	v_sub_f32_e32 v28, v210, v231
	v_exp_f32_e32 v28, v28
	v_add_f32_e32 v29, v25, v29
	v_add_f32_e32 v29, v26, v29
	v_add_f32_e32 v29, v27, v29
	v_add_f32_e32 v33, v28, v29
	v_sub_f32_e32 v29, v211, v231
	v_exp_f32_e32 v29, v29
	v_sub_f32_e32 v30, v208, v231
	v_exp_f32_e32 v30, v30
	v_sub_f32_e32 v31, v209, v231
	v_exp_f32_e32 v31, v31
	v_sub_f32_e32 v32, v206, v231
	v_exp_f32_e32 v32, v32
	v_add_f32_e32 v33, v29, v33
	v_add_f32_e32 v33, v30, v33
	v_add_f32_e32 v33, v31, v33
	v_add_f32_e32 v222, v32, v33
	v_sub_f32_e32 v223, v207, v231
	s_mov_b64 s[36:37], 0
